# static s_setprio 1 given to the other wave half (wr==0 instead of wr==1) in all 15 GEMM phases; on top of norm-loop consolidation
# speedup vs baseline: 1.0015x; 1.0015x over previous
; #define PG8_STAGE(bufoff, gbase, voff) do { if constexpr (!NOSTAGE) _Pragma("unroll") for (int _i = 0; _i < 2; ++_i) \
;         __builtin_amdgcn_global_load_lds((const unsigned*)((const char*)(gbase) + (size_t)_i * pstep##voff + v##voff), (PG8_LAS unsigned*)(lds + (bufoff) + ldsw + _i * 8192), 16, 0, 0); } while (0)
; #define PG8_WAIT_V(n) asm volatile("s_waitcnt vmcnt(" #n ")" ::: "memory")
; #define PG8_BAR __builtin_amdgcn_s_barrier()
; template <class Epi, class Sched, bool ALIGN_EPI = true, bool SP2 = true, bool FULLLINE = false, bool NOSTAGE = false, bool FP8 = false>
; __device__ __forceinline__ void gemm_phase(PG8_LAS unsigned char* lds, const Gemm g, const Sched& S, const Epi& E) {
;     ...
;     if (wr == 1) PG8_BAR;
;     PG8_WAIT_V(0); PG8_BAR;
;     PG8_BAR;
;     } else {
;     PG8_STAGE(PG8_SB(0, 0), cB, offB); PG8_STAGE(PG8_SA(0, 0), cA, offA); PG8_STAGE(PG8_SB(0, 1), cB + hstepB, offB); PG8_STAGE(PG8_SA(0, 1), cA + hstepA, offA);
;     if (wr == 1) PG8_BAR;
;     PG8_WAIT_V(4); PG8_BAR;
;     PG8_STAGE(PG8_SB(1, 0), cB + kstep, offB); PG8_STAGE(PG8_SA(1, 0), cA + kstep, offA); PG8_STAGE(PG8_SB(1, 1), cB + hstepB + kstep, offB);
;     PG8_WAIT_V(6); PG8_BAR;
;     }
;     if (wr == 1) __builtin_amdgcn_s_setprio(1);
.LBB0_254:
	s_waitcnt vmcnt(0)
	v_cndmask_b32_e64 v4, 0, 1, s[8:9]
	v_cmp_ne_u32_e64 s[6:7], 1, v4
	s_andn2_b64 vcc, exec, s[8:9]
	s_barrier
	s_barrier
	s_cbranch_vccz .LBB0_256
	s_setprio 1

; #define PG8_STAGE(bufoff, gbase, voff) do { if constexpr (!NOSTAGE) _Pragma("unroll") for (int _i = 0; _i < 2; ++_i) \
;         __builtin_amdgcn_global_load_lds((const unsigned*)((const char*)(gbase) + (size_t)_i * pstep##voff + v##voff), (PG8_LAS unsigned*)(lds + (bufoff) + ldsw + _i * 8192), 16, 0, 0); } while (0)
; #define PG8_WAIT_V(n) asm volatile("s_waitcnt vmcnt(" #n ")" ::: "memory")
; #define PG8_BAR __builtin_amdgcn_s_barrier()
; template <class Epi, class Sched, bool ALIGN_EPI = true, bool SP2 = true, bool FULLLINE = false, bool NOSTAGE = false, bool FP8 = false>
; __device__ __forceinline__ void gemm_phase(PG8_LAS unsigned char* lds, const Gemm g, const Sched& S, const Epi& E) {
;     ...
;     if (wr == 1) PG8_BAR;
;     PG8_WAIT_V(0); PG8_BAR;
;     PG8_BAR;
;     } else {
;     PG8_STAGE(PG8_SB(0, 0), cB, offB); PG8_STAGE(PG8_SA(0, 0), cA, offA); PG8_STAGE(PG8_SB(0, 1), cB + hstepB, offB); PG8_STAGE(PG8_SA(0, 1), cA + hstepA, offA);
;     if (wr == 1) PG8_BAR;
;     PG8_WAIT_V(4); PG8_BAR;
;     PG8_STAGE(PG8_SB(1, 0), cB + kstep, offB); PG8_STAGE(PG8_SA(1, 0), cA + kstep, offA); PG8_STAGE(PG8_SB(1, 1), cB + hstepB + kstep, offB);
;     PG8_WAIT_V(6); PG8_BAR;
;     }
;     if (wr == 1) __builtin_amdgcn_s_setprio(1);
.LBB0_582:
	s_waitcnt vmcnt(0)
	v_cndmask_b32_e64 v4, 0, 1, s[10:11]
	v_cmp_ne_u32_e64 s[6:7], 1, v4
	s_andn2_b64 vcc, exec, s[10:11]
	s_barrier
	s_barrier
	s_cbranch_vccz .LBB0_584
	s_setprio 1

; #define PG8_STAGE(bufoff, gbase, voff) do { if constexpr (!NOSTAGE) _Pragma("unroll") for (int _i = 0; _i < 2; ++_i) \
;         __builtin_amdgcn_global_load_lds((const unsigned*)((const char*)(gbase) + (size_t)_i * pstep##voff + v##voff), (PG8_LAS unsigned*)(lds + (bufoff) + ldsw + _i * 8192), 16, 0, 0); } while (0)
; #define PG8_WAIT_V(n) asm volatile("s_waitcnt vmcnt(" #n ")" ::: "memory")
; #define PG8_BAR __builtin_amdgcn_s_barrier()
; template <class Epi, class Sched, bool ALIGN_EPI = true, bool SP2 = true, bool FULLLINE = false, bool NOSTAGE = false, bool FP8 = false>
; __device__ __forceinline__ void gemm_phase(PG8_LAS unsigned char* lds, const Gemm g, const Sched& S, const Epi& E) {
;     ...
;     if (wr == 1) PG8_BAR;
;     PG8_WAIT_V(0); PG8_BAR;
;     PG8_BAR;
;     } else {
;     PG8_STAGE(PG8_SB(0, 0), cB, offB); PG8_STAGE(PG8_SA(0, 0), cA, offA); PG8_STAGE(PG8_SB(0, 1), cB + hstepB, offB); PG8_STAGE(PG8_SA(0, 1), cA + hstepA, offA);
;     if (wr == 1) PG8_BAR;
;     PG8_WAIT_V(4); PG8_BAR;
;     PG8_STAGE(PG8_SB(1, 0), cB + kstep, offB); PG8_STAGE(PG8_SA(1, 0), cA + kstep, offA); PG8_STAGE(PG8_SB(1, 1), cB + hstepB + kstep, offB);
;     PG8_WAIT_V(6); PG8_BAR;
;     }
;     if (wr == 1) __builtin_amdgcn_s_setprio(1);
.LBB0_854:
	s_waitcnt vmcnt(0)
	v_cndmask_b32_e64 v4, 0, 1, s[8:9]
	s_lshr_b32 s13, s6, 3
	v_cmp_ne_u32_e64 s[6:7], 1, v4
	s_andn2_b64 vcc, exec, s[8:9]
	s_barrier
	s_barrier
	s_cbranch_vccz .LBB0_856
	s_setprio 1
